# attn loop: counted waits + 4 hoisted V-reads, QK chains de-interleaved with split row-max tree, leaner K/V staging address math
# speedup vs baseline: 1.0309x; 1.0026x over previous
; #define LAS __attribute__((address_space(3)))
; #define SLOAD(i, t) do { const long k0_ = KROW(t); sg[i].a0 = *(const bf16x8*)(KVh + (k0_ + sr) * 1024 + sc); sg[i].a1 = *(const bf16x8*)(KVh + (k0_ + 32 + sr) * 1024 + sc); \
;     sg[i].rp = *(const bf16x8*)(KR + (k0_ + rr) * 32 + rc); } while (0)
; #define SWRITE_AT(boff, i) do { *(LAS bf16x8*)(lds + (boff) + st0) = sg[i].a0; *(LAS bf16x8*)(lds + (boff) + st1) = sg[i].a1; *(LAS bf16x8*)(lds + (boff) + st2) = sg[i].rp; } while (0)
; __device__ __forceinline__ void attn_unit(const bf16_t* __restrict__ Qb, bool rope_q, int tq0, const bf16_t* __restrict__ KVh, const bf16_t* __restrict__ KR,
;                                           int ctx_row0, int lat_row0, int NT, bf16_t* __restrict__ Ob, LAS unsigned char* lds, int wave_s) {
;     ...
;   const int trail = (wave_s >= 4) ? 1 : 0;
;   const LAS unsigned char* Kb = lds + OFF_K;
;   f32x16 p0, p1; float alpha; bf16x8 pa0, pa1, pa2, pa3;
;   SLOAD(0, 0); SLOAD(1, 1);
;   asm volatile("s_waitcnt vmcnt(3)" ::: "memory"); SWRITE_AT(0, 0);
;   if (trail) { asm volatile("s_waitcnt vmcnt(0)" ::: "memory"); SWRITE_AT(BUFB, 1); SLOAD(1, 2); SLOAD(0, 3); }
;   else { SLOAD(0, 2); }
;   __syncthreads();
;   if (trail) __syncthreads();
;   int bV = 0, bK = 0, bN = BUFB, bNN = 2 * BUFB;
.LBB0_523:
	v_add_f32_e32 v66, v159, v66
	v_add_f32_e32 v70, v179, v70
	v_add_f32_e32 v67, v160, v67
	v_add_f32_e32 v66, v70, v66
	v_add_f32_e32 v70, v180, v71
	v_add_f32_e32 v68, v161, v68
	v_add_f32_e32 v67, v70, v67
	v_add_f32_e32 v70, v181, v72
	v_add_f32_e32 v69, v178, v69
	v_add_f32_e32 v68, v70, v68
	v_add_f32_e32 v70, v182, v73
	v_add_f32_e32 v69, v70, v69
	v_add_f32_e32 v70, v183, v74
	v_add_f32_e32 v66, v70, v66
	v_add_f32_e32 v70, v184, v75
	v_add_f32_e32 v67, v70, v67
	v_add_f32_e32 v70, v185, v76
	v_add_f32_e32 v68, v70, v68
	v_add_f32_e32 v70, v186, v77
	v_add_f32_e32 v69, v70, v69
	v_add_f32_e32 v70, v187, v78
	v_add_f32_e32 v66, v70, v66
	v_add_f32_e32 v70, v188, v79
	v_add_f32_e32 v67, v70, v67
	v_add_f32_e32 v70, v189, v80
	v_add_f32_e32 v68, v70, v68
	v_add_f32_e32 v70, v190, v81
	v_add_f32_e32 v69, v70, v69
	v_add_f32_e32 v66, v67, v66
	v_add_f32_e32 v67, v69, v68
	v_add_f32_e32 v66, v67, v66
	v_add_f32_e32 v157, v157, v66
	v_add_u32_e32 v66, s64, v131
	v_readlane_b32 s0, v255, 14
	s_waitcnt vmcnt(3)
	s_waitcnt vmcnt(3)
	ds_write_b128 v66, v[126:129]
	v_add_u32_e32 v66, s64, v133
	s_or_b32 s0, s4, s0
	ds_write_b128 v66, v[122:125]
	v_add_u32_e32 v66, s64, v145
	s_ashr_i32 s1, s0, 31
	ds_write_b128 v66, v[118:121] offset:49152
	v_lshl_add_u64 v[66:67], v[134:135], 0, s[0:1]
	v_lshlrev_b64 v[66:67], 11, v[66:67]
	v_lshl_add_u64 v[66:67], v[138:139], 0, v[66:67]
	global_load_dwordx4 v[118:121], v[66:67], off
	v_lshl_add_u64 v[66:67], v[136:137], 0, s[0:1]
	v_lshlrev_b64 v[66:67], 11, v[66:67]
	v_lshl_add_u64 v[66:67], v[138:139], 0, v[66:67]
	global_load_dwordx4 v[122:125], v[66:67], off
	v_mov_b32_e32 v67, s1
	v_or_b32_e32 v66, s0, v144
	v_lshlrev_b64 v[66:67], 6, v[66:67]
	v_lshl_add_u64 v[66:67], v[140:141], 0, v[66:67]
	global_load_dwordx4 v[126:129], v[66:67], off
	v_lshlrev_b64 v[216:217], 11, v[134:135]
	v_lshlrev_b64 v[218:219], 11, v[136:137]
	v_lshlrev_b32_e32 v220, 6, v144
	v_mov_b32_e32 v221, 0
	v_lshl_add_u64 v[216:217], v[138:139], 0, v[216:217]
	v_lshl_add_u64 v[218:219], v[138:139], 0, v[218:219]
	v_lshl_add_u64 v[220:221], v[140:141], 0, v[220:221]
	s_addk_i32 s4, 0xff80
	s_mov_b32 s5, 0x8000
	s_mov_b32 s10, 0
	s_movk_i32 s0, 0x4000
	s_mov_b32 s11, 2
	s_waitcnt lgkmcnt(0)
	s_barrier

; #define LAS __attribute__((address_space(3)))
; __device__ __forceinline__ void qkt(f32x16& p0, f32x16& p1, const LAS unsigned char* Ks, const bf16x8* qr, const f32x16& negm, int r32, int hi) {
;   bf16x8 kf[12];
; #pragma unroll
;   for (int d0 = 0; d0 < 6; ++d0) { const int cb = (d0 * 16 + hi * 8) * 2;
;     kf[2 * d0] = *(const LAS bf16x8*)(Ks + KSWZ(r32, cb)); kf[2 * d0 + 1] = *(const LAS bf16x8*)(Ks + KSWZ(32 + r32, cb)); }
;   SBAR();
;   p0 = __builtin_amdgcn_mfma_f32_32x32x16_bf16(kf[0], qr[0], negm, 0, 0, 0); p1 = __builtin_amdgcn_mfma_f32_32x32x16_bf16(kf[1], qr[0], negm, 0, 0, 0);
; #pragma unroll
;   for (int d0 = 1; d0 < 6; ++d0) { p0 = __builtin_amdgcn_mfma_f32_32x32x16_bf16(kf[2 * d0], qr[d0], p0, 0, 0, 0); p1 = __builtin_amdgcn_mfma_f32_32x32x16_bf16(kf[2 * d0 + 1], qr[d0], p1, 0, 0, 0); }
; }
; __device__ __forceinline__ int v_st(int k, int c) { const int kk = (k & ~0xC) | ((k & 4) << 1) | ((k & 8) >> 1); return ((kk >> 3) * 4 + (c >> 5)) * 512 + ((kk & 7) * 32 + (c & 31)) * 2; }
; __device__ __forceinline__ int v_rd_base(int lane) { return ((lane & 3) << 3) | (((lane >> 2) & 3) << 6) | (((lane >> 4) & 1) << 5) | (((lane >> 5) & 1) << 8); }
; template <int OFF> __device__ __forceinline__ s16x4 tr_read(int vb) {
;   s16x4 r; asm volatile("ds_read_b64_tr_b16 %0, %1 offset:%2" : "=&v"(r) : "v"(vb), "i"(OFF) : "memory"); return r;
; }
; __device__ __forceinline__ void pv_d0(f32x16* o, int vb, bf16x8 pa0, bf16x8 pa1, bf16x8 pa2, bf16x8 pa3) {
;   const s16x4 a0 = tr_read<v_rd_off(0, 0, 0)>(vb), b0 = tr_read<v_rd_off(0, 0, 1)>(vb), a1 = tr_read<v_rd_off(0, 1, 0)>(vb), b1 = tr_read<v_rd_off(0, 1, 1)>(vb);
;   const s16x4 a2 = tr_read<v_rd_off(0, 2, 0)>(vb), b2 = tr_read<v_rd_off(0, 2, 1)>(vb), a3 = tr_read<v_rd_off(0, 3, 0)>(vb), b3 = tr_read<v_rd_off(0, 3, 1)>(vb);
;   const s16x4 c0 = tr_read<v_rd_off(1, 0, 0)>(vb), d0 = tr_read<v_rd_off(1, 0, 1)>(vb), c1 = tr_read<v_rd_off(1, 1, 0)>(vb), d1 = tr_read<v_rd_off(1, 1, 1)>(vb);
;   const s16x4 c2 = tr_read<v_rd_off(1, 2, 0)>(vb), d2 = tr_read<v_rd_off(1, 2, 1)>(vb), c3 = tr_read<v_rd_off(1, 3, 0)>(vb), d3 = tr_read<v_rd_off(1, 3, 1)>(vb);
;   asm volatile("s_waitcnt lgkmcnt(0)" ::: "memory"); SBAR();
;     ...
;   o[0] = __builtin_amdgcn_mfma_f32_32x32x16_bf16(pa0, PK(a0, b0), o[0], 0, 0, 0); o[1] = __builtin_amdgcn_mfma_f32_32x32x16_bf16(pa0, PK(c0, d0), o[1], 0, 0, 0);
.Lmy_attn_m1:
	ds_read_b64_tr_b16 v[70:71], v174 offset:0x1000
	ds_read_b64_tr_b16 v[72:73], v174 offset:0x1800
	ds_read_b64_tr_b16 v[162:163], v174 offset:0x1200
	ds_read_b64_tr_b16 v[164:165], v174 offset:0x1a00
	ds_read_b64_tr_b16 v[74:75], v174 offset:0x2000
	ds_read_b64_tr_b16 v[76:77], v174 offset:0x2800
	ds_read_b64_tr_b16 v[166:167], v174 offset:0x2200
	ds_read_b64_tr_b16 v[168:169], v174 offset:0x2a00
	ds_read_b64_tr_b16 v[78:79], v174 offset:0x3000
	ds_read_b64_tr_b16 v[80:81], v174 offset:0x3800
	ds_read_b64_tr_b16 v[170:171], v174 offset:0x3200
	ds_read_b64_tr_b16 v[172:173], v174 offset:0x3a00
	s_waitcnt lgkmcnt(14)
	v_mfma_f32_32x32x16_bf16 v[34:49], v[62:65], v[66:69], v[34:49]
	s_waitcnt lgkmcnt(12)
	v_mfma_f32_32x32x16_bf16 v[18:33], v[62:65], v[158:161], v[18:33]
	s_waitcnt lgkmcnt(10)
	v_mfma_f32_32x32x16_bf16 v[34:49], v[50:53], v[70:73], v[34:49]
	s_waitcnt lgkmcnt(8)
	v_mfma_f32_32x32x16_bf16 v[18:33], v[50:53], v[162:165], v[18:33]
	s_waitcnt lgkmcnt(6)
	v_mfma_f32_32x32x16_bf16 v[34:49], v[54:57], v[74:77], v[34:49]
	s_waitcnt lgkmcnt(4)
	v_mfma_f32_32x32x16_bf16 v[18:33], v[54:57], v[166:169], v[18:33]
	v_add_u32_e32 v54, s5, v146
	v_add_u32_e32 v55, v54, v147
	ds_read_b128 v[50:53], v55 offset:49152
	ds_read_b128 v[158:161], v55 offset:57344
	v_add_u32_e32 v55, v54, v148
	ds_read_b128 v[162:165], v55 offset:49152
	ds_read_b128 v[166:169], v55 offset:57344
	v_add_u32_e32 v55, v54, v149
	s_waitcnt lgkmcnt(6)
	v_mfma_f32_32x32x16_bf16 v[34:49], v[58:61], v[78:81], v[34:49]
	s_waitcnt lgkmcnt(4)
	v_mfma_f32_32x32x16_bf16 v[18:33], v[58:61], v[170:173], v[18:33]
	ds_read_b128 v[170:173], v55 offset:49152
	ds_read_b128 v[178:181], v55 offset:57344
	v_add_u32_e32 v55, v54, v150
	ds_read_b128 v[182:185], v55 offset:49152
	ds_read_b128 v[186:189], v55 offset:57344
	v_add_u32_e32 v55, v54, v151
	v_add_u32_e32 v54, v54, v152
	ds_read_b128 v[190:193], v55 offset:49152
	ds_read_b128 v[194:197], v55 offset:57344
	ds_read_b128 v[198:201], v54 offset:49152
	ds_read_b128 v[202:205], v54 offset:57344
	s_waitcnt lgkmcnt(11)
	v_mfma_f32_32x32x16_bf16 v[66:81], v[50:53], v[82:85], v[2:17]
	s_waitcnt lgkmcnt(9)
	v_mfma_f32_32x32x16_bf16 v[66:81], v[162:165], v[86:89], v[66:81]
	s_waitcnt lgkmcnt(7)
	v_mfma_f32_32x32x16_bf16 v[66:81], v[170:173], v[90:93], v[66:81]
	s_waitcnt lgkmcnt(5)
	v_mfma_f32_32x32x16_bf16 v[66:81], v[182:185], v[94:97], v[66:81]
	s_waitcnt lgkmcnt(3)
	v_mfma_f32_32x32x16_bf16 v[66:81], v[190:193], v[98:101], v[66:81]
	s_waitcnt lgkmcnt(1)
	v_mfma_f32_32x32x16_bf16 v[66:81], v[198:201], v[102:105], v[66:81]
	s_waitcnt lgkmcnt(0)
	v_mfma_f32_32x32x16_bf16 v[50:65], v[158:161], v[82:85], v[2:17]
	v_mfma_f32_32x32x16_bf16 v[50:65], v[166:169], v[86:89], v[50:65]
	v_mfma_f32_32x32x16_bf16 v[50:65], v[178:181], v[90:93], v[50:65]
	v_mfma_f32_32x32x16_bf16 v[50:65], v[186:189], v[94:97], v[50:65]
	v_mfma_f32_32x32x16_bf16 v[50:65], v[194:197], v[98:101], v[50:65]
	v_mfma_f32_32x32x16_bf16 v[50:65], v[202:205], v[102:105], v[50:65]
	s_setprio 0
	v_max3_f32 v158, v66, v67, v68
	v_max3_f32 v159, v69, v70, v71
	v_max3_f32 v158, v158, v72, v73
	v_max3_f32 v159, v159, v74, v75
	v_max3_f32 v158, v158, v76, v77
	v_max3_f32 v159, v159, v78, v79
	v_max3_f32 v158, v158, v80, v81
	s_nop 3
	v_max3_f32 v159, v159, v50, v51
	v_max3_f32 v158, v158, v52, v53
	v_max3_f32 v159, v159, v54, v55
	v_max3_f32 v158, v158, v56, v57
	v_max3_f32 v159, v159, v58, v59
	v_max3_f32 v158, v158, v60, v61
	v_max3_f32 v159, v159, v62, v63
	v_max3_f32 v158, v158, v64, v65
	v_max_f32_e32 v158, v158, v159
	v_mov_b32_e32 v159, v158
	s_nop 1
	v_permlane32_swap_b32_e32 v158, v159
	v_max_f32_e32 v159, v158, v159
	v_cmp_ge_f32_e32 vcc, s93, v159
	s_cmp_eq_u64 vcc, exec
	v_mov_b32_e32 v158, 1.0
	s_barrier
	s_cbranch_scc0 .LBB0_540
.LBB0_525:
	v_exp_f32_e32 v66, v66
	v_exp_f32_e32 v159, v50
	v_exp_f32_e32 v67, v67
	v_exp_f32_e32 v160, v51
	v_exp_f32_e32 v68, v68
	v_exp_f32_e32 v161, v52
	v_exp_f32_e32 v69, v69
	v_exp_f32_e32 v178, v53
	v_exp_f32_e32 v70, v70
	v_exp_f32_e32 v179, v54
	v_exp_f32_e32 v71, v71
	v_exp_f32_e32 v180, v55
	v_exp_f32_e32 v72, v72
	v_exp_f32_e32 v181, v56
	v_exp_f32_e32 v73, v73
	v_exp_f32_e32 v182, v57
	v_exp_f32_e32 v74, v74
	v_exp_f32_e32 v183, v58
	v_exp_f32_e32 v75, v75
	v_exp_f32_e32 v184, v59
	v_exp_f32_e32 v76, v76
	v_exp_f32_e32 v185, v60
	v_exp_f32_e32 v77, v77
	v_exp_f32_e32 v186, v61
	v_exp_f32_e32 v78, v78
	v_exp_f32_e32 v187, v62
	v_exp_f32_e32 v79, v79
	v_exp_f32_e32 v188, v63
	v_exp_f32_e32 v80, v80
	v_exp_f32_e32 v189, v64
	v_exp_f32_e32 v81, v81
	v_exp_f32_e32 v190, v65
	v_cvt_pk_bf16_f32 v54, v66, v67
	v_cvt_pk_bf16_f32 v55, v68, v69
	v_cvt_pk_bf16_f32 v56, v70, v71
	v_cvt_pk_bf16_f32 v57, v72, v73
	v_cvt_pk_bf16_f32 v50, v74, v75
	v_cvt_pk_bf16_f32 v51, v76, v77
	v_cvt_pk_bf16_f32 v52, v78, v79
	v_cvt_pk_bf16_f32 v53, v80, v81
	v_cvt_pk_bf16_f32 v58, v159, v160
	v_cvt_pk_bf16_f32 v59, v161, v178
	v_cvt_pk_bf16_f32 v60, v179, v180
	v_cvt_pk_bf16_f32 v61, v181, v182
	v_cvt_pk_bf16_f32 v62, v183, v184
	v_cvt_pk_bf16_f32 v63, v185, v186
	v_cvt_pk_bf16_f32 v64, v187, v188
	v_cvt_pk_bf16_f32 v65, v189, v190
	v_permlane32_swap_b32_e32 v54, v56
	v_permlane32_swap_b32_e32 v55, v57
	v_permlane32_swap_b32_e32 v50, v52
	v_permlane32_swap_b32_e32 v51, v53
	v_permlane32_swap_b32_e32 v58, v60
	v_permlane32_swap_b32_e32 v59, v61
	v_permlane32_swap_b32_e32 v62, v64
	v_permlane32_swap_b32_e32 v63, v65
	v_cmp_gt_f32_e32 vcc, 1.0, v158
	s_cbranch_vccz .LBB0_529
	s_and_saveexec_b64 s[0:1], s[2:3]
	ds_write_b32 v155, v158
	s_or_b64 exec, exec, s[0:1]
	s_waitcnt lgkmcnt(0)
	v_add_u32_e32 v158, v154, v132
	ds_read_b128 v[162:165], v158 offset:96
	ds_read_b128 v[166:169], v158 offset:64
	ds_read_b128 v[170:173], v158 offset:32
	ds_read_b128 v[192:195], v158
	s_waitcnt lgkmcnt(3)
	v_pk_mul_f32 v[46:47], v[46:47], v[162:163]
	s_waitcnt lgkmcnt(2)
	v_pk_mul_f32 v[42:43], v[42:43], v[166:167]
	s_waitcnt lgkmcnt(1)
	v_pk_mul_f32 v[38:39], v[38:39], v[170:171]
	v_pk_mul_f32 v[48:49], v[48:49], v[164:165]
	v_pk_mul_f32 v[44:45], v[44:45], v[168:169]
	v_pk_mul_f32 v[40:41], v[40:41], v[172:173]
	s_waitcnt lgkmcnt(0)
	v_pk_mul_f32 v[36:37], v[36:37], v[194:195]
	v_pk_mul_f32 v[34:35], v[34:35], v[192:193]
	v_pk_mul_f32 v[30:31], v[30:31], v[162:163]
	v_pk_mul_f32 v[26:27], v[26:27], v[166:167]
	v_pk_mul_f32 v[22:23], v[22:23], v[170:171]
	v_pk_mul_f32 v[32:33], v[32:33], v[164:165]
	v_pk_mul_f32 v[28:29], v[28:29], v[168:169]
	v_pk_mul_f32 v[24:25], v[24:25], v[172:173]
	v_pk_mul_f32 v[20:21], v[20:21], v[194:195]
	v_pk_mul_f32 v[18:19], v[18:19], v[192:193]
; #define LAS __attribute__((address_space(3)))
; __device__ __forceinline__ void qkt(f32x16& p0, f32x16& p1, const LAS unsigned char* Ks, const bf16x8* qr, const f32x16& negm, int r32, int hi) {
;   bf16x8 kf[12];
; #pragma unroll
;   for (int d0 = 0; d0 < 6; ++d0) { const int cb = (d0 * 16 + hi * 8) * 2;
;     kf[2 * d0] = *(const LAS bf16x8*)(Ks + KSWZ(r32, cb)); kf[2 * d0 + 1] = *(const LAS bf16x8*)(Ks + KSWZ(32 + r32, cb)); }
;   SBAR();
;   p0 = __builtin_amdgcn_mfma_f32_32x32x16_bf16(kf[0], qr[0], negm, 0, 0, 0); p1 = __builtin_amdgcn_mfma_f32_32x32x16_bf16(kf[1], qr[0], negm, 0, 0, 0);
; #pragma unroll
;   for (int d0 = 1; d0 < 6; ++d0) { p0 = __builtin_amdgcn_mfma_f32_32x32x16_bf16(kf[2 * d0], qr[d0], p0, 0, 0, 0); p1 = __builtin_amdgcn_mfma_f32_32x32x16_bf16(kf[2 * d0 + 1], qr[d0], p1, 0, 0, 0); }
; }
; __device__ __forceinline__ int v_st(int k, int c) { const int kk = (k & ~0xC) | ((k & 4) << 1) | ((k & 8) >> 1); return ((kk >> 3) * 4 + (c >> 5)) * 512 + ((kk & 7) * 32 + (c & 31)) * 2; }
; __device__ __forceinline__ int v_rd_base(int lane) { return ((lane & 3) << 3) | (((lane >> 2) & 3) << 6) | (((lane >> 4) & 1) << 5) | (((lane >> 5) & 1) << 8); }
; template <int OFF> __device__ __forceinline__ s16x4 tr_read(int vb) {
;   s16x4 r; asm volatile("ds_read_b64_tr_b16 %0, %1 offset:%2" : "=&v"(r) : "v"(vb), "i"(OFF) : "memory"); return r;
; }
; __device__ __forceinline__ void pv_d0(f32x16* o, int vb, bf16x8 pa0, bf16x8 pa1, bf16x8 pa2, bf16x8 pa3) {
;   const s16x4 a0 = tr_read<v_rd_off(0, 0, 0)>(vb), b0 = tr_read<v_rd_off(0, 0, 1)>(vb), a1 = tr_read<v_rd_off(0, 1, 0)>(vb), b1 = tr_read<v_rd_off(0, 1, 1)>(vb);
;   const s16x4 a2 = tr_read<v_rd_off(0, 2, 0)>(vb), b2 = tr_read<v_rd_off(0, 2, 1)>(vb), a3 = tr_read<v_rd_off(0, 3, 0)>(vb), b3 = tr_read<v_rd_off(0, 3, 1)>(vb);
;   const s16x4 c0 = tr_read<v_rd_off(1, 0, 0)>(vb), d0 = tr_read<v_rd_off(1, 0, 1)>(vb), c1 = tr_read<v_rd_off(1, 1, 0)>(vb), d1 = tr_read<v_rd_off(1, 1, 1)>(vb);
;   const s16x4 c2 = tr_read<v_rd_off(1, 2, 0)>(vb), d2 = tr_read<v_rd_off(1, 2, 1)>(vb), c3 = tr_read<v_rd_off(1, 3, 0)>(vb), d3 = tr_read<v_rd_off(1, 3, 1)>(vb);
;   asm volatile("s_waitcnt lgkmcnt(0)" ::: "memory"); SBAR();
;     ...
;   o[0] = __builtin_amdgcn_mfma_f32_32x32x16_bf16(pa0, PK(a0, b0), o[0], 0, 0, 0); o[1] = __builtin_amdgcn_mfma_f32_32x32x16_bf16(pa0, PK(c0, d0), o[1], 0, 0, 0);
.LBB0_529:
	s_add_i32 s23, s65, s11
	s_add_i32 s0, s23, 1
	s_cmpk_gt_u32 s0, 0x83
	s_cbranch_scc1 .LBB0_531
	s_and_b64 s[24:25], s[54:55], exec
	s_cselect_b32 s1, s22, s10
	s_min_u32 s0, s0, 0x81
	v_add_u32_e32 v158, s1, v131
	s_lshl_b32 s0, s0, 6
	s_waitcnt vmcnt(0)
	ds_write_b128 v158, v[106:109]
	v_add_u32_e32 v106, s1, v133
	s_add_i32 s0, s4, s0
	ds_write_b128 v106, v[110:113]
	v_add_u32_e32 v106, s1, v145
	s_ashr_i32 s1, s0, 31
	ds_write_b128 v106, v[114:117] offset:49152
	s_lshl_b64 s[100:101], s[0:1], 11
	v_lshl_add_u64 v[106:107], v[216:217], 0, s[100:101]
	v_lshl_add_u64 v[110:111], v[218:219], 0, s[100:101]
	s_lshl_b64 s[100:101], s[0:1], 6
	v_lshl_add_u64 v[114:115], v[220:221], 0, s[100:101]
	global_load_dwordx4 v[106:109], v[106:107], off
	s_nop 0
	global_load_dwordx4 v[110:113], v[110:111], off
	s_nop 0
	global_load_dwordx4 v[114:117], v[114:115], off
.LBB0_531:
	v_add_f32_e32 v66, v159, v66
	v_add_f32_e32 v70, v179, v70
	v_add_f32_e32 v67, v160, v67
	v_add_f32_e32 v66, v70, v66
	v_add_f32_e32 v70, v180, v71
	v_add_f32_e32 v68, v161, v68
	v_add_f32_e32 v67, v70, v67
	v_add_f32_e32 v70, v181, v72
	v_add_f32_e32 v69, v178, v69
	v_add_f32_e32 v68, v70, v68
	v_add_f32_e32 v70, v182, v73
	v_add_f32_e32 v69, v70, v69
	v_add_f32_e32 v70, v183, v74
	v_add_f32_e32 v66, v70, v66
	v_add_f32_e32 v70, v184, v75
	v_add_f32_e32 v67, v70, v67
	v_add_f32_e32 v70, v185, v76
	v_add_f32_e32 v68, v70, v68
	v_add_f32_e32 v70, v186, v77
	v_add_f32_e32 v69, v70, v69
	v_add_f32_e32 v70, v187, v78
	v_add_f32_e32 v66, v70, v66
	v_add_f32_e32 v70, v188, v79
	v_add_f32_e32 v67, v70, v67
	v_add_f32_e32 v70, v189, v80
	v_add_f32_e32 v68, v70, v68
	v_add_f32_e32 v70, v190, v81
	v_add_f32_e32 v69, v70, v69
	v_add_f32_e32 v66, v67, v66
	v_add_f32_e32 v67, v69, v68
	v_add_f32_e32 v66, v67, v66
	v_add_f32_e32 v157, v157, v66
	v_add_u32_e32 v174, s5, v156
	ds_read_b64_tr_b16 v[66:67], v174 offset:0
	ds_read_b64_tr_b16 v[68:69], v174 offset:0x800
	ds_read_b64_tr_b16 v[158:159], v174 offset:0x200
	ds_read_b64_tr_b16 v[160:161], v174 offset:0xa00
	s_waitcnt lgkmcnt(4)
	s_barrier
	s_setprio 2
	ds_read_b64_tr_b16 v[70:71], v174 offset:0x1000
	ds_read_b64_tr_b16 v[72:73], v174 offset:0x1800
	ds_read_b64_tr_b16 v[162:163], v174 offset:0x1200
	ds_read_b64_tr_b16 v[164:165], v174 offset:0x1a00
	ds_read_b64_tr_b16 v[74:75], v174 offset:0x2000
	ds_read_b64_tr_b16 v[76:77], v174 offset:0x2800
	ds_read_b64_tr_b16 v[166:167], v174 offset:0x2200
	ds_read_b64_tr_b16 v[168:169], v174 offset:0x2a00
	ds_read_b64_tr_b16 v[78:79], v174 offset:0x3000
	ds_read_b64_tr_b16 v[80:81], v174 offset:0x3800
	ds_read_b64_tr_b16 v[170:171], v174 offset:0x3200
	ds_read_b64_tr_b16 v[172:173], v174 offset:0x3a00
	s_waitcnt lgkmcnt(14)
	v_mfma_f32_32x32x16_bf16 v[34:49], v[54:57], v[66:69], v[34:49]
	s_waitcnt lgkmcnt(12)
	v_mfma_f32_32x32x16_bf16 v[18:33], v[54:57], v[158:161], v[18:33]
	v_add_u32_e32 v54, s10, v146
	v_add_u32_e32 v55, v54, v147
	s_waitcnt lgkmcnt(10)
	v_mfma_f32_32x32x16_bf16 v[34:49], v[50:53], v[70:73], v[34:49]
	s_waitcnt lgkmcnt(8)
	v_mfma_f32_32x32x16_bf16 v[18:33], v[50:53], v[162:165], v[18:33]
	ds_read_b128 v[50:53], v55 offset:49152
	ds_read_b128 v[158:161], v55 offset:57344
	v_add_u32_e32 v55, v54, v148
	s_waitcnt lgkmcnt(8)
	v_mfma_f32_32x32x16_bf16 v[34:49], v[58:61], v[74:77], v[34:49]
	s_waitcnt lgkmcnt(6)
	v_mfma_f32_32x32x16_bf16 v[18:33], v[58:61], v[166:169], v[18:33]
	ds_read_b128 v[162:165], v55 offset:49152
	ds_read_b128 v[166:169], v55 offset:57344
	v_add_u32_e32 v55, v54, v149
	s_waitcnt lgkmcnt(6)
	v_mfma_f32_32x32x16_bf16 v[34:49], v[62:65], v[78:81], v[34:49]
	s_waitcnt lgkmcnt(4)
	v_mfma_f32_32x32x16_bf16 v[18:33], v[62:65], v[170:173], v[18:33]
	ds_read_b128 v[170:173], v55 offset:49152
	ds_read_b128 v[178:181], v55 offset:57344
	v_add_u32_e32 v55, v54, v150
	ds_read_b128 v[182:185], v55 offset:49152
	ds_read_b128 v[186:189], v55 offset:57344
	v_add_u32_e32 v55, v54, v151
	v_add_u32_e32 v54, v54, v152
	ds_read_b128 v[190:193], v55 offset:49152
	ds_read_b128 v[194:197], v55 offset:57344
	ds_read_b128 v[198:201], v54 offset:49152
	ds_read_b128 v[202:205], v54 offset:57344
	s_waitcnt lgkmcnt(11)
	v_mfma_f32_32x32x16_bf16 v[66:81], v[50:53], v[82:85], v[2:17]
	s_waitcnt lgkmcnt(9)
	v_mfma_f32_32x32x16_bf16 v[66:81], v[162:165], v[86:89], v[66:81]
	s_waitcnt lgkmcnt(7)
	v_mfma_f32_32x32x16_bf16 v[66:81], v[170:173], v[90:93], v[66:81]
	s_waitcnt lgkmcnt(5)
	v_mfma_f32_32x32x16_bf16 v[66:81], v[182:185], v[94:97], v[66:81]
	s_waitcnt lgkmcnt(3)
	v_mfma_f32_32x32x16_bf16 v[66:81], v[190:193], v[98:101], v[66:81]
	s_waitcnt lgkmcnt(1)
	v_mfma_f32_32x32x16_bf16 v[66:81], v[198:201], v[102:105], v[66:81]
	s_waitcnt lgkmcnt(0)
	v_mfma_f32_32x32x16_bf16 v[50:65], v[158:161], v[82:85], v[2:17]
	v_mfma_f32_32x32x16_bf16 v[50:65], v[166:169], v[86:89], v[50:65]
	v_mfma_f32_32x32x16_bf16 v[50:65], v[178:181], v[90:93], v[50:65]
	v_mfma_f32_32x32x16_bf16 v[50:65], v[186:189], v[94:97], v[50:65]
	v_mfma_f32_32x32x16_bf16 v[50:65], v[194:197], v[98:101], v[50:65]
	v_mfma_f32_32x32x16_bf16 v[50:65], v[202:205], v[102:105], v[50:65]
	s_setprio 0
	v_max3_f32 v158, v66, v67, v68
	v_max3_f32 v159, v69, v70, v71
	v_max3_f32 v158, v158, v72, v73
	v_max3_f32 v159, v159, v74, v75
	v_max3_f32 v158, v158, v76, v77
	v_max3_f32 v159, v159, v78, v79
	v_max3_f32 v158, v158, v80, v81
	s_nop 3
	v_max3_f32 v159, v159, v50, v51
	v_max3_f32 v158, v158, v52, v53
	v_max3_f32 v159, v159, v54, v55
	v_max3_f32 v158, v158, v56, v57
	v_max3_f32 v159, v159, v58, v59
	v_max3_f32 v158, v158, v60, v61
	v_max3_f32 v159, v159, v62, v63
	v_max3_f32 v158, v158, v64, v65
	v_max_f32_e32 v158, v158, v159
	v_mov_b32_e32 v159, v158
	s_nop 1
	v_permlane32_swap_b32_e32 v158, v159
	v_max_f32_e32 v159, v158, v159
	v_cmp_ge_f32_e32 vcc, s93, v159
	s_cmp_eq_u64 vcc, exec
	v_mov_b32_e32 v158, 1.0
	s_barrier
	s_cbranch_scc0 .LBB0_541
; #define LAS __attribute__((address_space(3)))
; #define SLOAD(i, t) do { const long k0_ = KROW(t); sg[i].a0 = *(const bf16x8*)(KVh + (k0_ + sr) * 1024 + sc); sg[i].a1 = *(const bf16x8*)(KVh + (k0_ + 32 + sr) * 1024 + sc); \
;     sg[i].rp = *(const bf16x8*)(KR + (k0_ + rr) * 32 + rc); } while (0)
; #define SWRITE_AT(boff, i) do { *(LAS bf16x8*)(lds + (boff) + st0) = sg[i].a0; *(LAS bf16x8*)(lds + (boff) + st1) = sg[i].a1; *(LAS bf16x8*)(lds + (boff) + st2) = sg[i].rp; } while (0)
; #define PHASE_M(j) do { SBAR(); __builtin_amdgcn_s_setprio(2); if ((j) > 0) pv_d0(o, vb0 + bV, pa0, pa1, pa2, pa3); qkt(p0, p1, Kb + bK, qr, negm, r32, hi); __builtin_amdgcn_s_setprio(0); SBAR(); __syncthreads(); } while (0)
; __device__ __forceinline__ void softmaxT(f32x16& p0, f32x16& p1, float& mref, f32x16& negm, float& l_reg, float& alpha, bf16x8& pa0, bf16x8& pa1, bf16x8& pa2, bf16x8& pa3) {
;     ...
;   for (int r = 0; r < 16; ++r) { p0[r] = __builtin_amdgcn_exp2f(p0[r]); p1[r] = __builtin_amdgcn_exp2f(p1[r]); }
;   { float s0 = p0[0] + p1[0], s1 = p0[1] + p1[1], s2 = p0[2] + p1[2], s3 = p0[3] + p1[3];
; #pragma unroll
;     for (int r = 4; r < 16; r += 4) { s0 += p0[r] + p1[r]; s1 += p0[r + 1] + p1[r + 1]; s2 += p0[r + 2] + p1[r + 2]; s3 += p0[r + 3] + p1[r + 3]; }
;     l_reg += (s0 + s1) + (s2 + s3); }
;     ...
;   PK4(p0, 0, pa0); PK4(p0, 8, pa1); PK4(p1, 0, pa2); PK4(p1, 8, pa3);
; __device__ __forceinline__ void attn_unit(const bf16_t* __restrict__ Qb, bool rope_q, int tq0, const bf16_t* __restrict__ KVh, const bf16_t* __restrict__ KR,
;                                           int ctx_row0, int lat_row0, int NT, bf16_t* __restrict__ Ob, LAS unsigned char* lds, int wave_s) {
;     ...
;   const int trail = (wave_s >= 4) ? 1 : 0;
;   const LAS unsigned char* Kb = lds + OFF_K;
;   f32x16 p0, p1; float alpha; bf16x8 pa0, pa1, pa2, pa3;
;   SLOAD(0, 0); SLOAD(1, 1);
;   asm volatile("s_waitcnt vmcnt(3)" ::: "memory"); SWRITE_AT(0, 0);
;   if (trail) { asm volatile("s_waitcnt vmcnt(0)" ::: "memory"); SWRITE_AT(BUFB, 1); SLOAD(1, 2); SLOAD(0, 3); }
;   else { SLOAD(0, 2); }
;   __syncthreads();
;   if (trail) __syncthreads();
;   int bV = 0, bK = 0, bN = BUFB, bNN = 2 * BUFB;
;     ...
;   for (int j = 0; j < NT; j += 2) {
;     PHASE_M(j); PHASE_V(j, 1);
;     PHASE_M(j + 1); PHASE_V(j + 1, 0);
;   }
.LBB0_532:
	v_exp_f32_e32 v66, v66
	v_exp_f32_e32 v159, v50
	v_exp_f32_e32 v67, v67
	v_exp_f32_e32 v160, v51
	v_exp_f32_e32 v68, v68
	v_exp_f32_e32 v161, v52
	v_exp_f32_e32 v69, v69
	v_exp_f32_e32 v178, v53
	v_exp_f32_e32 v70, v70
	v_exp_f32_e32 v179, v54
	v_exp_f32_e32 v71, v71
	v_exp_f32_e32 v180, v55
	v_exp_f32_e32 v72, v72
	v_exp_f32_e32 v181, v56
	v_exp_f32_e32 v73, v73
	v_exp_f32_e32 v182, v57
	v_exp_f32_e32 v74, v74
	v_exp_f32_e32 v183, v58
	v_exp_f32_e32 v75, v75
	v_exp_f32_e32 v184, v59
	v_exp_f32_e32 v76, v76
	v_exp_f32_e32 v185, v60
	v_exp_f32_e32 v77, v77
	v_exp_f32_e32 v186, v61
	v_exp_f32_e32 v78, v78
	v_exp_f32_e32 v187, v62
	v_exp_f32_e32 v79, v79
	v_exp_f32_e32 v188, v63
	v_exp_f32_e32 v80, v80
	v_exp_f32_e32 v189, v64
	v_exp_f32_e32 v81, v81
	v_exp_f32_e32 v190, v65
	v_cvt_pk_bf16_f32 v62, v66, v67
	v_cvt_pk_bf16_f32 v63, v68, v69
	v_cvt_pk_bf16_f32 v64, v70, v71
	v_cvt_pk_bf16_f32 v65, v72, v73
	v_cvt_pk_bf16_f32 v50, v74, v75
	v_cvt_pk_bf16_f32 v51, v76, v77
	v_cvt_pk_bf16_f32 v52, v78, v79
	v_cvt_pk_bf16_f32 v53, v80, v81
	v_cvt_pk_bf16_f32 v54, v159, v160
	v_cvt_pk_bf16_f32 v55, v161, v178
	v_cvt_pk_bf16_f32 v56, v179, v180
	v_cvt_pk_bf16_f32 v57, v181, v182
	v_cvt_pk_bf16_f32 v58, v183, v184
	v_cvt_pk_bf16_f32 v59, v185, v186
	v_cvt_pk_bf16_f32 v60, v187, v188
	v_cvt_pk_bf16_f32 v61, v189, v190
	v_permlane32_swap_b32_e32 v62, v64
	v_permlane32_swap_b32_e32 v63, v65
	v_permlane32_swap_b32_e32 v50, v52
	v_permlane32_swap_b32_e32 v51, v53
	v_permlane32_swap_b32_e32 v54, v56
	v_permlane32_swap_b32_e32 v55, v57
	v_permlane32_swap_b32_e32 v58, v60
	v_permlane32_swap_b32_e32 v59, v61
	v_cmp_gt_f32_e32 vcc, 1.0, v158
	s_cbranch_vccz .LBB0_536
	s_and_saveexec_b64 s[0:1], s[2:3]
	ds_write_b32 v155, v158
	s_or_b64 exec, exec, s[0:1]
	s_waitcnt lgkmcnt(0)
	v_add_u32_e32 v158, v154, v132
	ds_read_b128 v[162:165], v158 offset:96
	ds_read_b128 v[166:169], v158 offset:64
	ds_read_b128 v[170:173], v158 offset:32
	ds_read_b128 v[192:195], v158
	s_waitcnt lgkmcnt(3)
	v_pk_mul_f32 v[46:47], v[46:47], v[162:163]
	s_waitcnt lgkmcnt(2)
	v_pk_mul_f32 v[42:43], v[42:43], v[166:167]
	s_waitcnt lgkmcnt(1)
	v_pk_mul_f32 v[38:39], v[38:39], v[170:171]
	v_pk_mul_f32 v[48:49], v[48:49], v[164:165]
	v_pk_mul_f32 v[44:45], v[44:45], v[168:169]
	v_pk_mul_f32 v[40:41], v[40:41], v[172:173]
	s_waitcnt lgkmcnt(0)
	v_pk_mul_f32 v[36:37], v[36:37], v[194:195]
	v_pk_mul_f32 v[34:35], v[34:35], v[192:193]
	v_pk_mul_f32 v[30:31], v[30:31], v[162:163]
	v_pk_mul_f32 v[26:27], v[26:27], v[166:167]
	v_pk_mul_f32 v[22:23], v[22:23], v[170:171]
	v_pk_mul_f32 v[32:33], v[32:33], v[164:165]
	v_pk_mul_f32 v[28:29], v[28:29], v[168:169]
	v_pk_mul_f32 v[24:25], v[24:25], v[172:173]
	v_pk_mul_f32 v[20:21], v[20:21], v[194:195]
	v_pk_mul_f32 v[18:19], v[18:19], v[192:193]
.LBB0_536:
	s_cmpk_gt_u32 s11, 0x81
	s_cselect_b64 s[0:1], -1, 0
	s_and_b64 vcc, exec, s[0:1]
	s_cbranch_vccnz .LBB0_538
	s_add_i32 s23, s23, 2
	s_and_b64 s[24:25], s[54:55], exec
	s_cselect_b32 s24, s5, s22
	v_add_u32_e32 v158, s24, v131
	s_min_u32 s23, s23, 0x81
	s_waitcnt vmcnt(0)
	ds_write_b128 v158, v[118:121]
	v_add_u32_e32 v118, s24, v133
	s_lshl_b32 s23, s23, 6
	ds_write_b128 v118, v[122:125]
	v_add_u32_e32 v118, s24, v145
	s_add_i32 s24, s4, s23
	s_ashr_i32 s25, s24, 31
	ds_write_b128 v118, v[126:129] offset:49152
	s_lshl_b64 s[100:101], s[24:25], 11
	v_lshl_add_u64 v[118:119], v[216:217], 0, s[100:101]
	v_lshl_add_u64 v[122:123], v[218:219], 0, s[100:101]
	s_lshl_b64 s[100:101], s[24:25], 6
	v_lshl_add_u64 v[126:127], v[220:221], 0, s[100:101]
	global_load_dwordx4 v[118:121], v[118:119], off
	s_nop 0
	global_load_dwordx4 v[122:125], v[122:123], off
	s_nop 0
	global_load_dwordx4 v[126:129], v[126:127], off
.LBB0_538:
	v_add_f32_e32 v66, v159, v66
	v_add_f32_e32 v70, v179, v70
	v_add_f32_e32 v67, v160, v67
	v_add_f32_e32 v66, v70, v66
	v_add_f32_e32 v70, v180, v71
	v_add_f32_e32 v68, v161, v68
	v_add_f32_e32 v67, v70, v67
	v_add_f32_e32 v70, v181, v72
	v_add_f32_e32 v69, v178, v69
	v_add_f32_e32 v68, v70, v68
	v_add_f32_e32 v70, v182, v73
	v_add_f32_e32 v69, v70, v69
	v_add_f32_e32 v70, v183, v74
	v_add_f32_e32 v66, v70, v66
	v_add_f32_e32 v70, v184, v75
	v_add_f32_e32 v67, v70, v67
	v_add_f32_e32 v70, v185, v76
	v_add_f32_e32 v68, v70, v68
	v_add_f32_e32 v70, v186, v77
	v_add_f32_e32 v69, v70, v69
	v_add_f32_e32 v70, v187, v78
	v_add_f32_e32 v66, v70, v66
	v_add_f32_e32 v70, v188, v79
	v_add_f32_e32 v67, v70, v67
	v_add_f32_e32 v70, v189, v80
	v_add_f32_e32 v68, v70, v68
	v_add_f32_e32 v70, v190, v81
	v_add_f32_e32 v69, v70, v69
	v_add_f32_e32 v66, v67, v66
	v_add_f32_e32 v67, v69, v68
	v_add_f32_e32 v66, v67, v66
	s_add_i32 s11, s11, 2
	v_add_f32_e32 v157, v157, v66
	s_and_b64 vcc, exec, s[0:1]
	v_add_u32_e32 v174, s10, v156
	ds_read_b64_tr_b16 v[66:67], v174 offset:0
	ds_read_b64_tr_b16 v[68:69], v174 offset:0x800
	ds_read_b64_tr_b16 v[158:159], v174 offset:0x200
	ds_read_b64_tr_b16 v[160:161], v174 offset:0xa00
	s_waitcnt lgkmcnt(4)
	s_barrier
	s_cbranch_vccnz .LBB0_542
	s_mov_b32 s0, s10
	s_mov_b32 s10, s5
	s_mov_b32 s5, s22
	s_mov_b32 s22, s0
	s_setprio 2
	s_branch .Lmy_attn_m1

; __global__ void __launch_bounds__(512, 2) fwd_megakernel(Params p) {
	.amdhsa_kernel _Z14fwd_megakernel6Params
		.amdhsa_group_segment_fixed_size 0
		.amdhsa_private_segment_fixed_size 0
		.amdhsa_kernarg_size 464
		.amdhsa_user_sgpr_count 2
		.amdhsa_user_sgpr_dispatch_ptr 0
		.amdhsa_user_sgpr_queue_ptr 0
		.amdhsa_user_sgpr_kernarg_segment_ptr 1
		.amdhsa_user_sgpr_dispatch_id 0
		.amdhsa_user_sgpr_kernarg_preload_length 0
		.amdhsa_user_sgpr_kernarg_preload_offset 0
		.amdhsa_user_sgpr_private_segment_size 0
		.amdhsa_uses_dynamic_stack 0
		.amdhsa_enable_private_segment 0
		.amdhsa_system_sgpr_workgroup_id_x 1
		.amdhsa_system_sgpr_workgroup_id_y 0
		.amdhsa_system_sgpr_workgroup_id_z 0
		.amdhsa_system_sgpr_workgroup_info 0
		.amdhsa_system_vgpr_workitem_id 2
		.amdhsa_next_free_vgpr 256
		.amdhsa_next_free_sgpr 102
		.amdhsa_accum_offset 256
		.amdhsa_reserve_vcc 1
		.amdhsa_float_round_mode_32 0
		.amdhsa_float_round_mode_16_64 0
		.amdhsa_float_denorm_mode_32 3
		.amdhsa_float_denorm_mode_16_64 3
		.amdhsa_dx10_clamp 1
		.amdhsa_ieee_mode 1
		.amdhsa_fp16_overflow 0
		.amdhsa_tg_split 0
		.amdhsa_exception_fp_ieee_invalid_op 0
		.amdhsa_exception_fp_denorm_src 0
		.amdhsa_exception_fp_ieee_div_zero 0
		.amdhsa_exception_fp_ieee_overflow 0
		.amdhsa_exception_fp_ieee_underflow 0
		.amdhsa_exception_fp_ieee_inexact 0
		.amdhsa_exception_int_div_zero 0
	.end_amdhsa_kernel

; __global__ void __launch_bounds__(512, 2) fwd_megakernel(Params p) {
amdhsa.kernels:
  - .agpr_count:     0
    .args:
      - .offset:         0
        .size:           208
        .value_kind:     by_value
      - .offset:         208
        .size:           4
        .value_kind:     hidden_block_count_x
      - .offset:         212
        .size:           4
        .value_kind:     hidden_block_count_y
      - .offset:         216
        .size:           4
        .value_kind:     hidden_block_count_z
      - .offset:         220
        .size:           2
        .value_kind:     hidden_group_size_x
      - .offset:         222
        .size:           2
        .value_kind:     hidden_group_size_y
      - .offset:         224
        .size:           2
        .value_kind:     hidden_group_size_z
      - .offset:         226
        .size:           2
        .value_kind:     hidden_remainder_x
      - .offset:         228
        .size:           2
        .value_kind:     hidden_remainder_y
      - .offset:         230
        .size:           2
        .value_kind:     hidden_remainder_z
      - .offset:         248
        .size:           8
        .value_kind:     hidden_global_offset_x
      - .offset:         256
        .size:           8
        .value_kind:     hidden_global_offset_y
      - .offset:         264
        .size:           8
        .value_kind:     hidden_global_offset_z
      - .offset:         272
        .size:           2
        .value_kind:     hidden_grid_dims
      - .offset:         296
        .size:           8
        .value_kind:     hidden_multigrid_sync_arg
      - .offset:         328
        .size:           4
        .value_kind:     hidden_dynamic_lds_size
    .group_segment_fixed_size: 0
    .kernarg_segment_align: 8
    .kernarg_segment_size: 464
    .language:       OpenCL C
    .language_version:
      - 2
      - 0
    .max_flat_workgroup_size: 512
    .name:           _Z14fwd_megakernel6Params
    .private_segment_fixed_size: 0
    .sgpr_count:     108
    .sgpr_spill_count: 34
    .symbol:         _Z14fwd_megakernel6Params.kd
    .uniform_work_group_size: 1
    .uses_dynamic_stack: false
    .vgpr_count:     256
    .vgpr_spill_count: 0
    .wavefront_size: 64
